# GEMM: accumulator zeroing (128 v_mov per tile) removed; first K-iteration of each tile runs from a loop-body copy whose first-touch MFMAs take C=0
# speedup vs baseline: 1.0053x; 1.0018x over previous
; #define PG8_STAGE(bufoff, gbase, voff) do { _Pragma("unroll") for (int _i = 0; _i < 2; ++_i) \
;         __builtin_amdgcn_global_load_lds((const unsigned*)((const char*)(gbase) + (voff)[_i]), (LAS unsigned*)(lds + (bufoff) + ldsw + _i * 8192), 16, 0, 0); } while (0)
; #define PG8_LDA(dst, b, h) do { _Pragma("unroll") for (int m = 0; m < 4; ++m) _Pragma("unroll") for (int k = 0; k < 2; ++k) dst[m][k] = *(const LAS bf16x8*)(lds + PG8_SA(b, h) + aoff + m * 2048 + k * 1024); } while (0)
; #define PG8_LDB(dst, b, h) do { _Pragma("unroll") for (int n = 0; n < 2; ++n) _Pragma("unroll") for (int k = 0; k < 2; ++k) dst[n][k] = *(const LAS bf16x8*)(lds + PG8_SB(b, h) + boff + n * 2048 + k * 1024); } while (0)
; #define PG8_MMA(ai, bj, At, Bt) do { __builtin_amdgcn_s_setprio(1); _Pragma("unroll") for (int m = 0; m < 4; ++m) _Pragma("unroll") for (int n = 0; n < 2; ++n) _Pragma("unroll") for (int k = 0; k < 2; ++k) \
;         acc[ai][bj][m][n] = __builtin_amdgcn_mfma_f32_16x16x32_bf16(Bt[n][k], At[m][k], acc[ai][bj][m][n], 0, 0, 0); __builtin_amdgcn_s_setprio(0); } while (0)
; template <class Epi>
; __device__ __forceinline__ void gemm_phase(LAS unsigned char* lds, const Gemm g, const StaticOrder& S, const Epi& E, const int tid) {
;     ...
;         for (int t = 0; t < nt; t += 2) {
;             const bool last = (t == nt - 2);
;             const char* a1 = cA + (size_t)(t + 1) * kstep;
;             const char* a2 = last ? nA : cA + (size_t)(t + 2) * kstep; const char* b2 = last ? nB : cB + (size_t)(t + 2) * kstep;
;             const char* a3 = a2 + kstep; const char* b3 = b2 + kstep;
;             PG8_LDB(B0, 0, 0); PG8_LDB(B1, 0, 1); PG8_SCHED; PG8_LDA(At, 0, 0); PG8_STAGE(PG8_SA(1, 1), a1 + hstepA, voffA);
;             PG8_WAIT_V(8); PG8_WAIT_L(0); PG8_BAR; PG8_MMA(0, 0, At, B0); PG8_MMA(0, 1, At, B1); PG8_BAR; PG8_SCHED;
;             PG8_LDA(At, 0, 1); PG8_STAGE(PG8_SB(0, 0), b2, voffB); PG8_STAGE(PG8_SB(0, 1), b2 + hstepB, voffB); PG8_STAGE(PG8_SA(0, 0), a2, voffA);
;             PG8_WAIT_V(8); PG8_WAIT_L(0); PG8_BAR; PG8_MMA(1, 0, At, B0); PG8_MMA(1, 1, At, B1); PG8_BAR; PG8_SCHED;
;     ...
;         for (int a = 0; a < 2; ++a)
; #pragma unroll
;             for (int b = 0; b < 2; ++b)
; #pragma unroll
;                 for (int m = 0; m < 4; ++m)
; #pragma unroll
;                     for (int n = 0; n < 2; ++n) acc[a][b][m][n] = (f32x4){0.f, 0.f, 0.f, 0.f};
.LBB0_737:
	s_add_u32 s18, s18, 0x80
	s_addc_u32 s19, s19, 0
	s_add_u32 s23, s20, 0x100
	s_addc_u32 s29, s21, 0
	s_mov_b32 s20, 0
	s_branch .Lmy_peel0
.LBB0_738:
	s_add_i32 s34, s20, 2
	s_add_u32 s35, s18, 0x80
	s_addc_u32 s21, s19, 0
	s_add_i32 s41, 0, 0x10000
	s_cmp_eq_u32 s64, s20
	s_cselect_b32 s21, s15, s21
	s_cselect_b32 s20, s14, s35
	s_cselect_b32 s45, s17, s29
	s_cselect_b32 s44, s16, s23
	s_add_i32 s35, 0, 0x14000
	s_waitcnt lgkmcnt(0)
	s_add_i32 m0, s30, 0xc000
	s_nop 0
	global_load_lds_dwordx4 v150, s[18:19]
	s_add_i32 m0, s30, 0xe000
	s_nop 0
	global_load_lds_dwordx4 v152, s[18:19]
	v_add_u32_e32 v136, s41, v182
	ds_read_b128 v[128:131], v136
	ds_read_b128 v[132:135], v136 offset:1024
	ds_read_b128 v[156:159], v136 offset:2048
	ds_read_b128 v[160:163], v136 offset:3072
	v_add_u32_e32 v136, s35, v182
	ds_read_b128 v[164:167], v136
	ds_read_b128 v[168:171], v136 offset:1024
	ds_read_b128 v[172:175], v136 offset:2048
	ds_read_b128 v[176:179], v136 offset:3072
	ds_read_b128 v[190:193], v188
	ds_read_b128 v[194:197], v188 offset:1024
	ds_read_b128 v[198:201], v188 offset:2048
	ds_read_b128 v[202:205], v188 offset:3072
	ds_read_b128 v[206:209], v188 offset:4096
	ds_read_b128 v[224:227], v188 offset:5120
	ds_read_b128 v[228:231], v188 offset:6144
	ds_read_b128 v[232:235], v188 offset:7168
	s_waitcnt vmcnt(8)
	s_waitcnt lgkmcnt(0)
	s_barrier
	s_setprio 1
	s_waitcnt lgkmcnt(0)
	v_mfma_f32_16x16x32_bf16 v[124:127], v[128:131], v[190:193], v[124:127]
	v_mfma_f32_16x16x32_bf16 v[120:123], v[156:159], v[190:193], v[120:123]
	v_mfma_f32_16x16x32_bf16 v[108:111], v[128:131], v[198:201], v[108:111]
	v_mfma_f32_16x16x32_bf16 v[104:107], v[156:159], v[198:201], v[104:107]
	v_mfma_f32_16x16x32_bf16 v[92:95], v[128:131], v[206:209], v[92:95]
	v_mfma_f32_16x16x32_bf16 v[88:91], v[156:159], v[206:209], v[88:91]
	v_mfma_f32_16x16x32_bf16 v[76:79], v[128:131], v[228:231], v[76:79]
	v_mfma_f32_16x16x32_bf16 v[72:75], v[156:159], v[228:231], v[72:75]
	v_mfma_f32_16x16x32_bf16 v[124:127], v[132:135], v[194:197], v[124:127]
	v_mfma_f32_16x16x32_bf16 v[120:123], v[160:163], v[194:197], v[120:123]
	v_mfma_f32_16x16x32_bf16 v[108:111], v[132:135], v[202:205], v[108:111]
	v_mfma_f32_16x16x32_bf16 v[104:107], v[160:163], v[202:205], v[104:107]
	v_mfma_f32_16x16x32_bf16 v[92:95], v[132:135], v[224:227], v[92:95]
	v_mfma_f32_16x16x32_bf16 v[88:91], v[160:163], v[224:227], v[88:91]
	v_mfma_f32_16x16x32_bf16 v[76:79], v[132:135], v[232:235], v[76:79]
	v_mfma_f32_16x16x32_bf16 v[72:75], v[160:163], v[232:235], v[72:75]
	s_setprio 0
	s_setprio 1
	v_mfma_f32_16x16x32_bf16 v[116:119], v[164:167], v[190:193], v[116:119]
	v_mfma_f32_16x16x32_bf16 v[112:115], v[172:175], v[190:193], v[112:115]
	v_mfma_f32_16x16x32_bf16 v[100:103], v[164:167], v[198:201], v[100:103]
	v_mfma_f32_16x16x32_bf16 v[96:99], v[172:175], v[198:201], v[96:99]
	v_mfma_f32_16x16x32_bf16 v[84:87], v[164:167], v[206:209], v[84:87]
	v_mfma_f32_16x16x32_bf16 v[80:83], v[172:175], v[206:209], v[80:83]
	v_mfma_f32_16x16x32_bf16 v[68:71], v[164:167], v[228:231], v[68:71]
	v_mfma_f32_16x16x32_bf16 v[64:67], v[172:175], v[228:231], v[64:67]
	v_mfma_f32_16x16x32_bf16 v[116:119], v[168:171], v[194:197], v[116:119]
	v_mfma_f32_16x16x32_bf16 v[112:115], v[176:179], v[194:197], v[112:115]
	v_mfma_f32_16x16x32_bf16 v[100:103], v[168:171], v[202:205], v[100:103]
	v_mfma_f32_16x16x32_bf16 v[96:99], v[176:179], v[202:205], v[96:99]
	v_mfma_f32_16x16x32_bf16 v[84:87], v[168:171], v[224:227], v[84:87]
	v_mfma_f32_16x16x32_bf16 v[80:83], v[176:179], v[224:227], v[80:83]
	v_mfma_f32_16x16x32_bf16 v[68:71], v[168:171], v[232:235], v[68:71]
	v_mfma_f32_16x16x32_bf16 v[64:67], v[176:179], v[232:235], v[64:67]
	s_setprio 0
	s_barrier
	s_add_i32 s41, s41, s28
	s_mov_b32 m0, s41
	s_nop 0
	global_load_lds_dwordx4 v140, s[44:45]
	s_add_i32 m0, s41, 0x2000
	s_add_i32 s35, s35, s28
	global_load_lds_dwordx4 v144, s[44:45]
	s_add_u32 s44, s44, s26
	s_addc_u32 s45, s45, 0
	s_mov_b32 m0, s35
	s_nop 0
	global_load_lds_dwordx4 v140, s[44:45]
	s_add_i32 m0, s35, 0x2000
	s_nop 0
	global_load_lds_dwordx4 v144, s[44:45]
	s_mov_b32 m0, s30
	s_nop 0
	global_load_lds_dwordx4 v138, s[20:21]
	s_mov_b32 m0, s31
	s_nop 0
	global_load_lds_dwordx4 v142, s[20:21]
	ds_read_b128 v[190:193], v188 offset:16384
	ds_read_b128 v[194:197], v188 offset:17408
	ds_read_b128 v[198:201], v188 offset:18432
	ds_read_b128 v[202:205], v188 offset:19456
	ds_read_b128 v[206:209], v188 offset:20480
	ds_read_b128 v[224:227], v188 offset:21504
	ds_read_b128 v[228:231], v188 offset:22528
	ds_read_b128 v[232:235], v188 offset:23552
	s_waitcnt vmcnt(8)
	s_waitcnt lgkmcnt(0)
	s_barrier
; #define PG8_STAGE(bufoff, gbase, voff) do { _Pragma("unroll") for (int _i = 0; _i < 2; ++_i) \
;         __builtin_amdgcn_global_load_lds((const unsigned*)((const char*)(gbase) + (voff)[_i]), (LAS unsigned*)(lds + (bufoff) + ldsw + _i * 8192), 16, 0, 0); } while (0)
; #define PG8_LDA(dst, b, h) do { _Pragma("unroll") for (int m = 0; m < 4; ++m) _Pragma("unroll") for (int k = 0; k < 2; ++k) dst[m][k] = *(const LAS bf16x8*)(lds + PG8_SA(b, h) + aoff + m * 2048 + k * 1024); } while (0)
; #define PG8_LDB(dst, b, h) do { _Pragma("unroll") for (int n = 0; n < 2; ++n) _Pragma("unroll") for (int k = 0; k < 2; ++k) dst[n][k] = *(const LAS bf16x8*)(lds + PG8_SB(b, h) + boff + n * 2048 + k * 1024); } while (0)
; #define PG8_MMA(ai, bj, At, Bt) do { __builtin_amdgcn_s_setprio(1); _Pragma("unroll") for (int m = 0; m < 4; ++m) _Pragma("unroll") for (int n = 0; n < 2; ++n) _Pragma("unroll") for (int k = 0; k < 2; ++k) \
;         acc[ai][bj][m][n] = __builtin_amdgcn_mfma_f32_16x16x32_bf16(Bt[n][k], At[m][k], acc[ai][bj][m][n], 0, 0, 0); __builtin_amdgcn_s_setprio(0); } while (0)
; #define PG8_WAIT_V(n) asm volatile("s_waitcnt vmcnt(" #n ")" ::: "memory")
; #define PG8_WAIT_L(n) asm volatile("s_waitcnt lgkmcnt(" #n ")" ::: "memory")
; #define PG8_BAR __builtin_amdgcn_s_barrier()
; #define PG8_SCHED __builtin_amdgcn_sched_barrier(0)
; template <class Epi>
; __device__ __forceinline__ void gemm_phase(LAS unsigned char* lds, const Gemm g, const StaticOrder& S, const Epi& E, const int tid) {
;     ...
;             PG8_LDA(At, 0, 1); PG8_STAGE(PG8_SB(0, 0), b2, voffB); PG8_STAGE(PG8_SB(0, 1), b2 + hstepB, voffB); PG8_STAGE(PG8_SA(0, 0), a2, voffA);
;             PG8_WAIT_V(8); PG8_WAIT_L(0); PG8_BAR; PG8_MMA(1, 0, At, B0); PG8_MMA(1, 1, At, B1); PG8_BAR; PG8_SCHED;
;             PG8_LDB(B0, 1, 0); PG8_LDB(B1, 1, 1); PG8_SCHED; PG8_LDA(At, 1, 0); PG8_STAGE(PG8_SA(0, 1), a2 + hstepA, voffA);
;             PG8_WAIT_V(8); PG8_WAIT_L(0); PG8_BAR; PG8_MMA(0, 0, At, B0); PG8_MMA(0, 1, At, B1); PG8_BAR; PG8_SCHED;
	s_setprio 1
	s_waitcnt lgkmcnt(0)
	v_mfma_f32_16x16x32_bf16 v[60:63], v[128:131], v[190:193], v[60:63]
	v_mfma_f32_16x16x32_bf16 v[56:59], v[156:159], v[190:193], v[56:59]
	v_mfma_f32_16x16x32_bf16 v[44:47], v[128:131], v[198:201], v[44:47]
	v_mfma_f32_16x16x32_bf16 v[40:43], v[156:159], v[198:201], v[40:43]
	v_mfma_f32_16x16x32_bf16 v[28:31], v[128:131], v[206:209], v[28:31]
	v_mfma_f32_16x16x32_bf16 v[24:27], v[156:159], v[206:209], v[24:27]
	v_mfma_f32_16x16x32_bf16 v[12:15], v[128:131], v[228:231], v[12:15]
	v_mfma_f32_16x16x32_bf16 v[8:11], v[156:159], v[228:231], v[8:11]
	v_mfma_f32_16x16x32_bf16 v[60:63], v[132:135], v[194:197], v[60:63]
	v_mfma_f32_16x16x32_bf16 v[56:59], v[160:163], v[194:197], v[56:59]
	v_mfma_f32_16x16x32_bf16 v[44:47], v[132:135], v[202:205], v[44:47]
	v_mfma_f32_16x16x32_bf16 v[40:43], v[160:163], v[202:205], v[40:43]
	v_mfma_f32_16x16x32_bf16 v[28:31], v[132:135], v[224:227], v[28:31]
	v_mfma_f32_16x16x32_bf16 v[24:27], v[160:163], v[224:227], v[24:27]
	v_mfma_f32_16x16x32_bf16 v[12:15], v[132:135], v[232:235], v[12:15]
	v_mfma_f32_16x16x32_bf16 v[8:11], v[160:163], v[232:235], v[8:11]
	s_setprio 0
	s_setprio 1
	v_mfma_f32_16x16x32_bf16 v[52:55], v[164:167], v[190:193], v[52:55]
	v_mfma_f32_16x16x32_bf16 v[48:51], v[172:175], v[190:193], v[48:51]
	v_mfma_f32_16x16x32_bf16 v[36:39], v[164:167], v[198:201], v[36:39]
	v_mfma_f32_16x16x32_bf16 v[32:35], v[172:175], v[198:201], v[32:35]
	v_mfma_f32_16x16x32_bf16 v[20:23], v[164:167], v[206:209], v[20:23]
	v_mfma_f32_16x16x32_bf16 v[16:19], v[172:175], v[206:209], v[16:19]
	v_mfma_f32_16x16x32_bf16 v[4:7], v[164:167], v[228:231], v[4:7]
	v_mfma_f32_16x16x32_bf16 v[0:3], v[172:175], v[228:231], v[0:3]
	v_mfma_f32_16x16x32_bf16 v[52:55], v[168:171], v[194:197], v[52:55]
	v_mfma_f32_16x16x32_bf16 v[48:51], v[176:179], v[194:197], v[48:51]
	v_mfma_f32_16x16x32_bf16 v[36:39], v[168:171], v[202:205], v[36:39]
	v_mfma_f32_16x16x32_bf16 v[32:35], v[176:179], v[202:205], v[32:35]
	v_mfma_f32_16x16x32_bf16 v[20:23], v[168:171], v[224:227], v[20:23]
	v_mfma_f32_16x16x32_bf16 v[16:19], v[176:179], v[224:227], v[16:19]
	v_mfma_f32_16x16x32_bf16 v[4:7], v[168:171], v[232:235], v[4:7]
	v_mfma_f32_16x16x32_bf16 v[0:3], v[176:179], v[232:235], v[0:3]
	s_setprio 0
	s_barrier
	s_add_i32 s35, 0, 0x18000
	s_add_i32 s41, 0, 0x1c000
	s_add_u32 s20, s20, s80
	s_addc_u32 s21, s21, 0
	s_mov_b32 m0, s38
	s_nop 0
	global_load_lds_dwordx4 v138, s[20:21]
	s_mov_b32 m0, s39
	s_nop 0
	global_load_lds_dwordx4 v142, s[20:21]
	v_add_u32_e32 v155, s35, v182
	ds_read_b128 v[128:131], v155
	ds_read_b128 v[132:135], v155 offset:1024
	ds_read_b128 v[156:159], v155 offset:2048
	ds_read_b128 v[160:163], v155 offset:3072
	v_add_u32_e32 v155, s41, v182
	ds_read_b128 v[164:167], v155
	ds_read_b128 v[168:171], v155 offset:1024
	ds_read_b128 v[172:175], v155 offset:2048
	ds_read_b128 v[176:179], v155 offset:3072
	ds_read_b128 v[190:193], v188 offset:32768
	ds_read_b128 v[194:197], v188 offset:33792
	ds_read_b128 v[198:201], v188 offset:34816
	ds_read_b128 v[202:205], v188 offset:35840
	ds_read_b128 v[206:209], v188 offset:36864
	ds_read_b128 v[224:227], v188 offset:37888
	ds_read_b128 v[228:231], v188 offset:38912
	ds_read_b128 v[232:235], v188 offset:39936
	s_waitcnt vmcnt(8)
	s_waitcnt lgkmcnt(0)
	s_barrier
	s_setprio 1
	s_waitcnt lgkmcnt(0)
	v_mfma_f32_16x16x32_bf16 v[124:127], v[128:131], v[190:193], v[124:127]
	v_mfma_f32_16x16x32_bf16 v[120:123], v[156:159], v[190:193], v[120:123]
	v_mfma_f32_16x16x32_bf16 v[108:111], v[128:131], v[198:201], v[108:111]
	v_mfma_f32_16x16x32_bf16 v[104:107], v[156:159], v[198:201], v[104:107]
	v_mfma_f32_16x16x32_bf16 v[92:95], v[128:131], v[206:209], v[92:95]
	v_mfma_f32_16x16x32_bf16 v[88:91], v[156:159], v[206:209], v[88:91]
	v_mfma_f32_16x16x32_bf16 v[76:79], v[128:131], v[228:231], v[76:79]
	v_mfma_f32_16x16x32_bf16 v[72:75], v[156:159], v[228:231], v[72:75]
	v_mfma_f32_16x16x32_bf16 v[124:127], v[132:135], v[194:197], v[124:127]
	v_mfma_f32_16x16x32_bf16 v[120:123], v[160:163], v[194:197], v[120:123]
	v_mfma_f32_16x16x32_bf16 v[108:111], v[132:135], v[202:205], v[108:111]
	v_mfma_f32_16x16x32_bf16 v[104:107], v[160:163], v[202:205], v[104:107]
	v_mfma_f32_16x16x32_bf16 v[92:95], v[132:135], v[224:227], v[92:95]
	v_mfma_f32_16x16x32_bf16 v[88:91], v[160:163], v[224:227], v[88:91]
	v_mfma_f32_16x16x32_bf16 v[76:79], v[132:135], v[232:235], v[76:79]
	v_mfma_f32_16x16x32_bf16 v[72:75], v[160:163], v[232:235], v[72:75]
	s_setprio 0
	s_setprio 1
	v_mfma_f32_16x16x32_bf16 v[116:119], v[164:167], v[190:193], v[116:119]
	v_mfma_f32_16x16x32_bf16 v[112:115], v[172:175], v[190:193], v[112:115]
	v_mfma_f32_16x16x32_bf16 v[100:103], v[164:167], v[198:201], v[100:103]
	v_mfma_f32_16x16x32_bf16 v[96:99], v[172:175], v[198:201], v[96:99]
	v_mfma_f32_16x16x32_bf16 v[84:87], v[164:167], v[206:209], v[84:87]
	v_mfma_f32_16x16x32_bf16 v[80:83], v[172:175], v[206:209], v[80:83]
	v_mfma_f32_16x16x32_bf16 v[68:71], v[164:167], v[228:231], v[68:71]
	v_mfma_f32_16x16x32_bf16 v[64:67], v[172:175], v[228:231], v[64:67]
	v_mfma_f32_16x16x32_bf16 v[116:119], v[168:171], v[194:197], v[116:119]
	v_mfma_f32_16x16x32_bf16 v[112:115], v[176:179], v[194:197], v[112:115]
	v_mfma_f32_16x16x32_bf16 v[100:103], v[168:171], v[202:205], v[100:103]
	v_mfma_f32_16x16x32_bf16 v[96:99], v[176:179], v[202:205], v[96:99]
	v_mfma_f32_16x16x32_bf16 v[84:87], v[168:171], v[224:227], v[84:87]
	v_mfma_f32_16x16x32_bf16 v[80:83], v[176:179], v[224:227], v[80:83]
	v_mfma_f32_16x16x32_bf16 v[68:71], v[168:171], v[232:235], v[68:71]
	v_mfma_f32_16x16x32_bf16 v[64:67], v[176:179], v[232:235], v[64:67]
	s_setprio 0
	s_barrier
; #define PG8_STAGE(bufoff, gbase, voff) do { _Pragma("unroll") for (int _i = 0; _i < 2; ++_i) \
;         __builtin_amdgcn_global_load_lds((const unsigned*)((const char*)(gbase) + (voff)[_i]), (LAS unsigned*)(lds + (bufoff) + ldsw + _i * 8192), 16, 0, 0); } while (0)
; #define PG8_LDA(dst, b, h) do { _Pragma("unroll") for (int m = 0; m < 4; ++m) _Pragma("unroll") for (int k = 0; k < 2; ++k) dst[m][k] = *(const LAS bf16x8*)(lds + PG8_SA(b, h) + aoff + m * 2048 + k * 1024); } while (0)
; #define PG8_LDB(dst, b, h) do { _Pragma("unroll") for (int n = 0; n < 2; ++n) _Pragma("unroll") for (int k = 0; k < 2; ++k) dst[n][k] = *(const LAS bf16x8*)(lds + PG8_SB(b, h) + boff + n * 2048 + k * 1024); } while (0)
; #define PG8_MMA(ai, bj, At, Bt) do { __builtin_amdgcn_s_setprio(1); _Pragma("unroll") for (int m = 0; m < 4; ++m) _Pragma("unroll") for (int n = 0; n < 2; ++n) _Pragma("unroll") for (int k = 0; k < 2; ++k) \
;         acc[ai][bj][m][n] = __builtin_amdgcn_mfma_f32_16x16x32_bf16(Bt[n][k], At[m][k], acc[ai][bj][m][n], 0, 0, 0); __builtin_amdgcn_s_setprio(0); } while (0)
; #define PG8_WAIT_V(n) asm volatile("s_waitcnt vmcnt(" #n ")" ::: "memory")
; #define PG8_WAIT_L(n) asm volatile("s_waitcnt lgkmcnt(" #n ")" ::: "memory")
; #define PG8_BAR __builtin_amdgcn_s_barrier()
; #define PG8_SCHED __builtin_amdgcn_sched_barrier(0)
; template <class Epi>
; __device__ __forceinline__ void gemm_phase(LAS unsigned char* lds, const Gemm g, const StaticOrder& S, const Epi& E, const int tid) {
;     ...
;             PG8_LDB(B0, 0, 0); PG8_LDB(B1, 0, 1); PG8_SCHED; PG8_LDA(At, 0, 0); PG8_STAGE(PG8_SA(1, 1), a1 + hstepA, voffA);
;     ...
;             PG8_LDA(At, 1, 1); PG8_STAGE(PG8_SB(1, 0), b3, voffB); PG8_STAGE(PG8_SB(1, 1), b3 + hstepB, voffB); PG8_STAGE(PG8_SA(1, 0), a3, voffA);
;             PG8_WAIT_V(8); PG8_WAIT_L(0); PG8_BAR; PG8_MMA(1, 0, At, B0); PG8_MMA(1, 1, At, B1); PG8_BAR; PG8_SCHED;
;         }
	s_add_i32 s100, s35, s28
	s_sub_i32 m0, s100, 0x80
	s_sub_u32 s44, s44, s26
	s_subb_u32 s45, s45, 0
	global_load_lds_dwordx4 v140, s[44:45] offset:128
	s_add_i32 m0, s100, 0x1f80
	s_add_i32 s100, s41, s28
	global_load_lds_dwordx4 v144, s[44:45] offset:128
	s_add_u32 s44, s44, s26
	s_addc_u32 s45, s45, 0
	s_sub_i32 m0, s100, 0x80
	s_nop 0
	global_load_lds_dwordx4 v140, s[44:45] offset:128
	s_add_i32 m0, s100, 0x1f80
	s_sub_u32 s20, s20, s80
	global_load_lds_dwordx4 v144, s[44:45] offset:128
	s_subb_u32 s21, s21, 0
	s_sub_i32 m0, s8, 0x80
	s_nop 0
	global_load_lds_dwordx4 v138, s[20:21] offset:128
	s_sub_i32 m0, s9, 0x80
	s_nop 0
	global_load_lds_dwordx4 v142, s[20:21] offset:128
	ds_read_b128 v[190:193], v188 offset:49152
	ds_read_b128 v[194:197], v188 offset:50176
	ds_read_b128 v[198:201], v188 offset:51200
	ds_read_b128 v[202:205], v188 offset:52224
	ds_read_b128 v[206:209], v188 offset:53248
	ds_read_b128 v[224:227], v188 offset:54272
	ds_read_b128 v[228:231], v188 offset:55296
	ds_read_b128 v[232:235], v188 offset:56320
	s_waitcnt vmcnt(8)
	s_waitcnt lgkmcnt(0)
	s_barrier
	s_setprio 1
	s_waitcnt lgkmcnt(0)
	v_mfma_f32_16x16x32_bf16 v[60:63], v[128:131], v[190:193], v[60:63]
	v_mfma_f32_16x16x32_bf16 v[56:59], v[156:159], v[190:193], v[56:59]
	v_mfma_f32_16x16x32_bf16 v[44:47], v[128:131], v[198:201], v[44:47]
	v_mfma_f32_16x16x32_bf16 v[40:43], v[156:159], v[198:201], v[40:43]
	v_mfma_f32_16x16x32_bf16 v[28:31], v[128:131], v[206:209], v[28:31]
	v_mfma_f32_16x16x32_bf16 v[24:27], v[156:159], v[206:209], v[24:27]
	v_mfma_f32_16x16x32_bf16 v[12:15], v[128:131], v[228:231], v[12:15]
	v_mfma_f32_16x16x32_bf16 v[8:11], v[156:159], v[228:231], v[8:11]
	v_mfma_f32_16x16x32_bf16 v[60:63], v[132:135], v[194:197], v[60:63]
	v_mfma_f32_16x16x32_bf16 v[56:59], v[160:163], v[194:197], v[56:59]
	v_mfma_f32_16x16x32_bf16 v[44:47], v[132:135], v[202:205], v[44:47]
	v_mfma_f32_16x16x32_bf16 v[40:43], v[160:163], v[202:205], v[40:43]
	v_mfma_f32_16x16x32_bf16 v[28:31], v[132:135], v[224:227], v[28:31]
	v_mfma_f32_16x16x32_bf16 v[24:27], v[160:163], v[224:227], v[24:27]
	v_mfma_f32_16x16x32_bf16 v[12:15], v[132:135], v[232:235], v[12:15]
	v_mfma_f32_16x16x32_bf16 v[8:11], v[160:163], v[232:235], v[8:11]
	s_setprio 0
	s_setprio 1
	v_mfma_f32_16x16x32_bf16 v[52:55], v[164:167], v[190:193], v[52:55]
	v_mfma_f32_16x16x32_bf16 v[48:51], v[172:175], v[190:193], v[48:51]
	v_mfma_f32_16x16x32_bf16 v[36:39], v[164:167], v[198:201], v[36:39]
	v_mfma_f32_16x16x32_bf16 v[32:35], v[172:175], v[198:201], v[32:35]
	v_mfma_f32_16x16x32_bf16 v[20:23], v[164:167], v[206:209], v[20:23]
	v_mfma_f32_16x16x32_bf16 v[16:19], v[172:175], v[206:209], v[16:19]
	v_mfma_f32_16x16x32_bf16 v[4:7], v[164:167], v[228:231], v[4:7]
	v_mfma_f32_16x16x32_bf16 v[0:3], v[172:175], v[228:231], v[0:3]
	v_mfma_f32_16x16x32_bf16 v[52:55], v[168:171], v[194:197], v[52:55]
	v_mfma_f32_16x16x32_bf16 v[48:51], v[176:179], v[194:197], v[48:51]
	v_mfma_f32_16x16x32_bf16 v[36:39], v[168:171], v[202:205], v[36:39]
	v_mfma_f32_16x16x32_bf16 v[32:35], v[176:179], v[202:205], v[32:35]
	v_mfma_f32_16x16x32_bf16 v[20:23], v[168:171], v[224:227], v[20:23]
	v_mfma_f32_16x16x32_bf16 v[16:19], v[176:179], v[224:227], v[16:19]
	v_mfma_f32_16x16x32_bf16 v[4:7], v[168:171], v[232:235], v[4:7]
	v_mfma_f32_16x16x32_bf16 v[0:3], v[176:179], v[232:235], v[0:3]
	s_setprio 0
	s_barrier
	s_add_u32 s18, s18, 0x100
	s_addc_u32 s19, s19, 0
	s_add_u32 s23, s23, 0x100
	s_addc_u32 s29, s29, 0
	s_cmp_ge_u32 s34, s12
	s_mov_b32 s20, s34
	s_cbranch_scc0 .LBB0_738
	s_branch .Lmy_kexit0
.Lmy_peel0:
	s_add_i32 s34, s20, 2
	s_add_u32 s35, s18, 0x80
	s_addc_u32 s21, s19, 0
	s_add_i32 s41, 0, 0x10000
	s_cmp_eq_u32 s64, s20
	s_cselect_b32 s21, s15, s21
	s_cselect_b32 s20, s14, s35
	s_cselect_b32 s45, s17, s29
	s_cselect_b32 s44, s16, s23
	s_add_i32 s35, 0, 0x14000
	s_waitcnt lgkmcnt(0)
	s_add_i32 m0, s30, 0xc000
	s_nop 0
	global_load_lds_dwordx4 v150, s[18:19]
	s_add_i32 m0, s30, 0xe000
	s_nop 0
	global_load_lds_dwordx4 v152, s[18:19]
	v_add_u32_e32 v136, s41, v182
	ds_read_b128 v[128:131], v136
	ds_read_b128 v[132:135], v136 offset:1024
	ds_read_b128 v[156:159], v136 offset:2048
	ds_read_b128 v[160:163], v136 offset:3072
	v_add_u32_e32 v136, s35, v182
	ds_read_b128 v[164:167], v136
	ds_read_b128 v[168:171], v136 offset:1024
	ds_read_b128 v[172:175], v136 offset:2048
	ds_read_b128 v[176:179], v136 offset:3072
	ds_read_b128 v[190:193], v188
	ds_read_b128 v[194:197], v188 offset:1024
	ds_read_b128 v[198:201], v188 offset:2048
	ds_read_b128 v[202:205], v188 offset:3072
	ds_read_b128 v[206:209], v188 offset:4096
	ds_read_b128 v[224:227], v188 offset:5120
	ds_read_b128 v[228:231], v188 offset:6144
	ds_read_b128 v[232:235], v188 offset:7168
	s_waitcnt vmcnt(8)
	s_waitcnt lgkmcnt(0)
	s_barrier
; #define PG8_STAGE(bufoff, gbase, voff) do { _Pragma("unroll") for (int _i = 0; _i < 2; ++_i) \
;         __builtin_amdgcn_global_load_lds((const unsigned*)((const char*)(gbase) + (voff)[_i]), (LAS unsigned*)(lds + (bufoff) + ldsw + _i * 8192), 16, 0, 0); } while (0)
; #define PG8_LDA(dst, b, h) do { _Pragma("unroll") for (int m = 0; m < 4; ++m) _Pragma("unroll") for (int k = 0; k < 2; ++k) dst[m][k] = *(const LAS bf16x8*)(lds + PG8_SA(b, h) + aoff + m * 2048 + k * 1024); } while (0)
; #define PG8_LDB(dst, b, h) do { _Pragma("unroll") for (int n = 0; n < 2; ++n) _Pragma("unroll") for (int k = 0; k < 2; ++k) dst[n][k] = *(const LAS bf16x8*)(lds + PG8_SB(b, h) + boff + n * 2048 + k * 1024); } while (0)
; #define PG8_MMA(ai, bj, At, Bt) do { __builtin_amdgcn_s_setprio(1); _Pragma("unroll") for (int m = 0; m < 4; ++m) _Pragma("unroll") for (int n = 0; n < 2; ++n) _Pragma("unroll") for (int k = 0; k < 2; ++k) \
;         acc[ai][bj][m][n] = __builtin_amdgcn_mfma_f32_16x16x32_bf16(Bt[n][k], At[m][k], acc[ai][bj][m][n], 0, 0, 0); __builtin_amdgcn_s_setprio(0); } while (0)
; #define PG8_WAIT_V(n) asm volatile("s_waitcnt vmcnt(" #n ")" ::: "memory")
; #define PG8_WAIT_L(n) asm volatile("s_waitcnt lgkmcnt(" #n ")" ::: "memory")
; #define PG8_BAR __builtin_amdgcn_s_barrier()
; #define PG8_SCHED __builtin_amdgcn_sched_barrier(0)
; template <class Epi>
; __device__ __forceinline__ void gemm_phase(LAS unsigned char* lds, const Gemm g, const StaticOrder& S, const Epi& E, const int tid) {
;     ...
;             PG8_LDB(B0, 0, 0); PG8_LDB(B1, 0, 1); PG8_SCHED; PG8_LDA(At, 0, 0); PG8_STAGE(PG8_SA(1, 1), a1 + hstepA, voffA);
;             PG8_WAIT_V(8); PG8_WAIT_L(0); PG8_BAR; PG8_MMA(0, 0, At, B0); PG8_MMA(0, 1, At, B1); PG8_BAR; PG8_SCHED;
;             PG8_LDA(At, 0, 1); PG8_STAGE(PG8_SB(0, 0), b2, voffB); PG8_STAGE(PG8_SB(0, 1), b2 + hstepB, voffB); PG8_STAGE(PG8_SA(0, 0), a2, voffA);
;             PG8_WAIT_V(8); PG8_WAIT_L(0); PG8_BAR; PG8_MMA(1, 0, At, B0); PG8_MMA(1, 1, At, B1); PG8_BAR; PG8_SCHED;
	s_setprio 1
	s_waitcnt lgkmcnt(0)
	v_mfma_f32_16x16x32_bf16 v[124:127], v[128:131], v[190:193], 0
	v_mfma_f32_16x16x32_bf16 v[120:123], v[156:159], v[190:193], 0
	v_mfma_f32_16x16x32_bf16 v[108:111], v[128:131], v[198:201], 0
	v_mfma_f32_16x16x32_bf16 v[104:107], v[156:159], v[198:201], 0
	v_mfma_f32_16x16x32_bf16 v[92:95], v[128:131], v[206:209], 0
	v_mfma_f32_16x16x32_bf16 v[88:91], v[156:159], v[206:209], 0
	v_mfma_f32_16x16x32_bf16 v[76:79], v[128:131], v[228:231], 0
	v_mfma_f32_16x16x32_bf16 v[72:75], v[156:159], v[228:231], 0
	v_mfma_f32_16x16x32_bf16 v[124:127], v[132:135], v[194:197], v[124:127]
	v_mfma_f32_16x16x32_bf16 v[120:123], v[160:163], v[194:197], v[120:123]
	v_mfma_f32_16x16x32_bf16 v[108:111], v[132:135], v[202:205], v[108:111]
	v_mfma_f32_16x16x32_bf16 v[104:107], v[160:163], v[202:205], v[104:107]
	v_mfma_f32_16x16x32_bf16 v[92:95], v[132:135], v[224:227], v[92:95]
	v_mfma_f32_16x16x32_bf16 v[88:91], v[160:163], v[224:227], v[88:91]
	v_mfma_f32_16x16x32_bf16 v[76:79], v[132:135], v[232:235], v[76:79]
	v_mfma_f32_16x16x32_bf16 v[72:75], v[160:163], v[232:235], v[72:75]
	s_setprio 0
	s_setprio 1
	v_mfma_f32_16x16x32_bf16 v[116:119], v[164:167], v[190:193], 0
	v_mfma_f32_16x16x32_bf16 v[112:115], v[172:175], v[190:193], 0
	v_mfma_f32_16x16x32_bf16 v[100:103], v[164:167], v[198:201], 0
	v_mfma_f32_16x16x32_bf16 v[96:99], v[172:175], v[198:201], 0
	v_mfma_f32_16x16x32_bf16 v[84:87], v[164:167], v[206:209], 0
	v_mfma_f32_16x16x32_bf16 v[80:83], v[172:175], v[206:209], 0
	v_mfma_f32_16x16x32_bf16 v[68:71], v[164:167], v[228:231], 0
	v_mfma_f32_16x16x32_bf16 v[64:67], v[172:175], v[228:231], 0
	v_mfma_f32_16x16x32_bf16 v[116:119], v[168:171], v[194:197], v[116:119]
	v_mfma_f32_16x16x32_bf16 v[112:115], v[176:179], v[194:197], v[112:115]
	v_mfma_f32_16x16x32_bf16 v[100:103], v[168:171], v[202:205], v[100:103]
	v_mfma_f32_16x16x32_bf16 v[96:99], v[176:179], v[202:205], v[96:99]
	v_mfma_f32_16x16x32_bf16 v[84:87], v[168:171], v[224:227], v[84:87]
	v_mfma_f32_16x16x32_bf16 v[80:83], v[176:179], v[224:227], v[80:83]
	v_mfma_f32_16x16x32_bf16 v[68:71], v[168:171], v[232:235], v[68:71]
	v_mfma_f32_16x16x32_bf16 v[64:67], v[176:179], v[232:235], v[64:67]
	s_setprio 0
	s_barrier
	s_add_i32 s41, s41, s28
	s_mov_b32 m0, s41
	s_nop 0
	global_load_lds_dwordx4 v140, s[44:45]
	s_add_i32 m0, s41, 0x2000
	s_add_i32 s35, s35, s28
	global_load_lds_dwordx4 v144, s[44:45]
	s_add_u32 s44, s44, s26
	s_addc_u32 s45, s45, 0
	s_mov_b32 m0, s35
	s_nop 0
	global_load_lds_dwordx4 v140, s[44:45]
	s_add_i32 m0, s35, 0x2000
	s_nop 0
	global_load_lds_dwordx4 v144, s[44:45]
	s_mov_b32 m0, s30
	s_nop 0
	global_load_lds_dwordx4 v138, s[20:21]
	s_mov_b32 m0, s31
	s_nop 0
	global_load_lds_dwordx4 v142, s[20:21]
	ds_read_b128 v[190:193], v188 offset:16384
	ds_read_b128 v[194:197], v188 offset:17408
	ds_read_b128 v[198:201], v188 offset:18432
	ds_read_b128 v[202:205], v188 offset:19456
	ds_read_b128 v[206:209], v188 offset:20480
	ds_read_b128 v[224:227], v188 offset:21504
	ds_read_b128 v[228:231], v188 offset:22528
	ds_read_b128 v[232:235], v188 offset:23552
	s_waitcnt vmcnt(8)
	s_waitcnt lgkmcnt(0)
	s_barrier
	s_setprio 1
	s_waitcnt lgkmcnt(0)
	v_mfma_f32_16x16x32_bf16 v[60:63], v[128:131], v[190:193], 0
	v_mfma_f32_16x16x32_bf16 v[56:59], v[156:159], v[190:193], 0
	v_mfma_f32_16x16x32_bf16 v[44:47], v[128:131], v[198:201], 0
	v_mfma_f32_16x16x32_bf16 v[40:43], v[156:159], v[198:201], 0
	v_mfma_f32_16x16x32_bf16 v[28:31], v[128:131], v[206:209], 0
	v_mfma_f32_16x16x32_bf16 v[24:27], v[156:159], v[206:209], 0
	v_mfma_f32_16x16x32_bf16 v[12:15], v[128:131], v[228:231], 0
	v_mfma_f32_16x16x32_bf16 v[8:11], v[156:159], v[228:231], 0
	v_mfma_f32_16x16x32_bf16 v[60:63], v[132:135], v[194:197], v[60:63]
	v_mfma_f32_16x16x32_bf16 v[56:59], v[160:163], v[194:197], v[56:59]
	v_mfma_f32_16x16x32_bf16 v[44:47], v[132:135], v[202:205], v[44:47]
	v_mfma_f32_16x16x32_bf16 v[40:43], v[160:163], v[202:205], v[40:43]
	v_mfma_f32_16x16x32_bf16 v[28:31], v[132:135], v[224:227], v[28:31]
	v_mfma_f32_16x16x32_bf16 v[24:27], v[160:163], v[224:227], v[24:27]
	v_mfma_f32_16x16x32_bf16 v[12:15], v[132:135], v[232:235], v[12:15]
	v_mfma_f32_16x16x32_bf16 v[8:11], v[160:163], v[232:235], v[8:11]
	s_setprio 0
	s_setprio 1
	v_mfma_f32_16x16x32_bf16 v[52:55], v[164:167], v[190:193], 0
	v_mfma_f32_16x16x32_bf16 v[48:51], v[172:175], v[190:193], 0
	v_mfma_f32_16x16x32_bf16 v[36:39], v[164:167], v[198:201], 0
	v_mfma_f32_16x16x32_bf16 v[32:35], v[172:175], v[198:201], 0
	v_mfma_f32_16x16x32_bf16 v[20:23], v[164:167], v[206:209], 0
	v_mfma_f32_16x16x32_bf16 v[16:19], v[172:175], v[206:209], 0
	v_mfma_f32_16x16x32_bf16 v[4:7], v[164:167], v[228:231], 0
	v_mfma_f32_16x16x32_bf16 v[0:3], v[172:175], v[228:231], 0
	v_mfma_f32_16x16x32_bf16 v[52:55], v[168:171], v[194:197], v[52:55]
	v_mfma_f32_16x16x32_bf16 v[48:51], v[176:179], v[194:197], v[48:51]
	v_mfma_f32_16x16x32_bf16 v[36:39], v[168:171], v[202:205], v[36:39]
	v_mfma_f32_16x16x32_bf16 v[32:35], v[176:179], v[202:205], v[32:35]
	v_mfma_f32_16x16x32_bf16 v[20:23], v[168:171], v[224:227], v[20:23]
	v_mfma_f32_16x16x32_bf16 v[16:19], v[176:179], v[224:227], v[16:19]
	v_mfma_f32_16x16x32_bf16 v[4:7], v[168:171], v[232:235], v[4:7]
	v_mfma_f32_16x16x32_bf16 v[0:3], v[176:179], v[232:235], v[0:3]
	s_setprio 0
	s_barrier
; #define PG8_STAGE(bufoff, gbase, voff) do { _Pragma("unroll") for (int _i = 0; _i < 2; ++_i) \
;         __builtin_amdgcn_global_load_lds((const unsigned*)((const char*)(gbase) + (voff)[_i]), (LAS unsigned*)(lds + (bufoff) + ldsw + _i * 8192), 16, 0, 0); } while (0)
; #define PG8_LDA(dst, b, h) do { _Pragma("unroll") for (int m = 0; m < 4; ++m) _Pragma("unroll") for (int k = 0; k < 2; ++k) dst[m][k] = *(const LAS bf16x8*)(lds + PG8_SA(b, h) + aoff + m * 2048 + k * 1024); } while (0)
; #define PG8_LDB(dst, b, h) do { _Pragma("unroll") for (int n = 0; n < 2; ++n) _Pragma("unroll") for (int k = 0; k < 2; ++k) dst[n][k] = *(const LAS bf16x8*)(lds + PG8_SB(b, h) + boff + n * 2048 + k * 1024); } while (0)
; #define PG8_MMA(ai, bj, At, Bt) do { __builtin_amdgcn_s_setprio(1); _Pragma("unroll") for (int m = 0; m < 4; ++m) _Pragma("unroll") for (int n = 0; n < 2; ++n) _Pragma("unroll") for (int k = 0; k < 2; ++k) \
;         acc[ai][bj][m][n] = __builtin_amdgcn_mfma_f32_16x16x32_bf16(Bt[n][k], At[m][k], acc[ai][bj][m][n], 0, 0, 0); __builtin_amdgcn_s_setprio(0); } while (0)
; #define PG8_WAIT_V(n) asm volatile("s_waitcnt vmcnt(" #n ")" ::: "memory")
; #define PG8_WAIT_L(n) asm volatile("s_waitcnt lgkmcnt(" #n ")" ::: "memory")
; #define PG8_BAR __builtin_amdgcn_s_barrier()
; #define PG8_SCHED __builtin_amdgcn_sched_barrier(0)
; template <class Epi>
; __device__ __forceinline__ void gemm_phase(LAS unsigned char* lds, const Gemm g, const StaticOrder& S, const Epi& E, const int tid) {
;     ...
;             PG8_LDB(B0, 1, 0); PG8_LDB(B1, 1, 1); PG8_SCHED; PG8_LDA(At, 1, 0); PG8_STAGE(PG8_SA(0, 1), a2 + hstepA, voffA);
;             PG8_WAIT_V(8); PG8_WAIT_L(0); PG8_BAR; PG8_MMA(0, 0, At, B0); PG8_MMA(0, 1, At, B1); PG8_BAR; PG8_SCHED;
;             PG8_LDA(At, 1, 1); PG8_STAGE(PG8_SB(1, 0), b3, voffB); PG8_STAGE(PG8_SB(1, 1), b3 + hstepB, voffB); PG8_STAGE(PG8_SA(1, 0), a3, voffA);
;             PG8_WAIT_V(8); PG8_WAIT_L(0); PG8_BAR; PG8_MMA(1, 0, At, B0); PG8_MMA(1, 1, At, B1); PG8_BAR; PG8_SCHED;
;         }
	s_add_i32 s35, 0, 0x18000
	s_add_i32 s41, 0, 0x1c000
	s_add_u32 s20, s20, s80
	s_addc_u32 s21, s21, 0
	s_mov_b32 m0, s38
	s_nop 0
	global_load_lds_dwordx4 v138, s[20:21]
	s_mov_b32 m0, s39
	s_nop 0
	global_load_lds_dwordx4 v142, s[20:21]
	v_add_u32_e32 v155, s35, v182
	ds_read_b128 v[128:131], v155
	ds_read_b128 v[132:135], v155 offset:1024
	ds_read_b128 v[156:159], v155 offset:2048
	ds_read_b128 v[160:163], v155 offset:3072
	v_add_u32_e32 v155, s41, v182
	ds_read_b128 v[164:167], v155
	ds_read_b128 v[168:171], v155 offset:1024
	ds_read_b128 v[172:175], v155 offset:2048
	ds_read_b128 v[176:179], v155 offset:3072
	ds_read_b128 v[190:193], v188 offset:32768
	ds_read_b128 v[194:197], v188 offset:33792
	ds_read_b128 v[198:201], v188 offset:34816
	ds_read_b128 v[202:205], v188 offset:35840
	ds_read_b128 v[206:209], v188 offset:36864
	ds_read_b128 v[224:227], v188 offset:37888
	ds_read_b128 v[228:231], v188 offset:38912
	ds_read_b128 v[232:235], v188 offset:39936
	s_waitcnt vmcnt(8)
	s_waitcnt lgkmcnt(0)
	s_barrier
	s_setprio 1
	s_waitcnt lgkmcnt(0)
	v_mfma_f32_16x16x32_bf16 v[124:127], v[128:131], v[190:193], v[124:127]
	v_mfma_f32_16x16x32_bf16 v[120:123], v[156:159], v[190:193], v[120:123]
	v_mfma_f32_16x16x32_bf16 v[108:111], v[128:131], v[198:201], v[108:111]
	v_mfma_f32_16x16x32_bf16 v[104:107], v[156:159], v[198:201], v[104:107]
	v_mfma_f32_16x16x32_bf16 v[92:95], v[128:131], v[206:209], v[92:95]
	v_mfma_f32_16x16x32_bf16 v[88:91], v[156:159], v[206:209], v[88:91]
	v_mfma_f32_16x16x32_bf16 v[76:79], v[128:131], v[228:231], v[76:79]
	v_mfma_f32_16x16x32_bf16 v[72:75], v[156:159], v[228:231], v[72:75]
	v_mfma_f32_16x16x32_bf16 v[124:127], v[132:135], v[194:197], v[124:127]
	v_mfma_f32_16x16x32_bf16 v[120:123], v[160:163], v[194:197], v[120:123]
	v_mfma_f32_16x16x32_bf16 v[108:111], v[132:135], v[202:205], v[108:111]
	v_mfma_f32_16x16x32_bf16 v[104:107], v[160:163], v[202:205], v[104:107]
	v_mfma_f32_16x16x32_bf16 v[92:95], v[132:135], v[224:227], v[92:95]
	v_mfma_f32_16x16x32_bf16 v[88:91], v[160:163], v[224:227], v[88:91]
	v_mfma_f32_16x16x32_bf16 v[76:79], v[132:135], v[232:235], v[76:79]
	v_mfma_f32_16x16x32_bf16 v[72:75], v[160:163], v[232:235], v[72:75]
	s_setprio 0
	s_setprio 1
	v_mfma_f32_16x16x32_bf16 v[116:119], v[164:167], v[190:193], v[116:119]
	v_mfma_f32_16x16x32_bf16 v[112:115], v[172:175], v[190:193], v[112:115]
	v_mfma_f32_16x16x32_bf16 v[100:103], v[164:167], v[198:201], v[100:103]
	v_mfma_f32_16x16x32_bf16 v[96:99], v[172:175], v[198:201], v[96:99]
	v_mfma_f32_16x16x32_bf16 v[84:87], v[164:167], v[206:209], v[84:87]
	v_mfma_f32_16x16x32_bf16 v[80:83], v[172:175], v[206:209], v[80:83]
	v_mfma_f32_16x16x32_bf16 v[68:71], v[164:167], v[228:231], v[68:71]
	v_mfma_f32_16x16x32_bf16 v[64:67], v[172:175], v[228:231], v[64:67]
	v_mfma_f32_16x16x32_bf16 v[116:119], v[168:171], v[194:197], v[116:119]
	v_mfma_f32_16x16x32_bf16 v[112:115], v[176:179], v[194:197], v[112:115]
	v_mfma_f32_16x16x32_bf16 v[100:103], v[168:171], v[202:205], v[100:103]
	v_mfma_f32_16x16x32_bf16 v[96:99], v[176:179], v[202:205], v[96:99]
	v_mfma_f32_16x16x32_bf16 v[84:87], v[168:171], v[224:227], v[84:87]
	v_mfma_f32_16x16x32_bf16 v[80:83], v[176:179], v[224:227], v[80:83]
	v_mfma_f32_16x16x32_bf16 v[68:71], v[168:171], v[232:235], v[68:71]
	v_mfma_f32_16x16x32_bf16 v[64:67], v[176:179], v[232:235], v[64:67]
	s_setprio 0
	s_barrier
	s_add_i32 s100, s35, s28
	s_sub_i32 m0, s100, 0x80
	s_sub_u32 s44, s44, s26
	s_subb_u32 s45, s45, 0
	global_load_lds_dwordx4 v140, s[44:45] offset:128
	s_add_i32 m0, s100, 0x1f80
	s_add_i32 s100, s41, s28
	global_load_lds_dwordx4 v144, s[44:45] offset:128
	s_add_u32 s44, s44, s26
	s_addc_u32 s45, s45, 0
	s_sub_i32 m0, s100, 0x80
	s_nop 0
	global_load_lds_dwordx4 v140, s[44:45] offset:128
	s_add_i32 m0, s100, 0x1f80
	s_sub_u32 s20, s20, s80
	global_load_lds_dwordx4 v144, s[44:45] offset:128
	s_subb_u32 s21, s21, 0
	s_sub_i32 m0, s8, 0x80
	s_nop 0
	global_load_lds_dwordx4 v138, s[20:21] offset:128
	s_sub_i32 m0, s9, 0x80
	s_nop 0
	global_load_lds_dwordx4 v142, s[20:21] offset:128
	ds_read_b128 v[190:193], v188 offset:49152
	ds_read_b128 v[194:197], v188 offset:50176
	ds_read_b128 v[198:201], v188 offset:51200
	ds_read_b128 v[202:205], v188 offset:52224
	ds_read_b128 v[206:209], v188 offset:53248
	ds_read_b128 v[224:227], v188 offset:54272
	ds_read_b128 v[228:231], v188 offset:55296
	ds_read_b128 v[232:235], v188 offset:56320
	s_waitcnt vmcnt(8)
	s_waitcnt lgkmcnt(0)
	s_barrier
	s_setprio 1
	s_waitcnt lgkmcnt(0)
	v_mfma_f32_16x16x32_bf16 v[60:63], v[128:131], v[190:193], v[60:63]
	v_mfma_f32_16x16x32_bf16 v[56:59], v[156:159], v[190:193], v[56:59]
	v_mfma_f32_16x16x32_bf16 v[44:47], v[128:131], v[198:201], v[44:47]
	v_mfma_f32_16x16x32_bf16 v[40:43], v[156:159], v[198:201], v[40:43]
	v_mfma_f32_16x16x32_bf16 v[28:31], v[128:131], v[206:209], v[28:31]
	v_mfma_f32_16x16x32_bf16 v[24:27], v[156:159], v[206:209], v[24:27]
	v_mfma_f32_16x16x32_bf16 v[12:15], v[128:131], v[228:231], v[12:15]
	v_mfma_f32_16x16x32_bf16 v[8:11], v[156:159], v[228:231], v[8:11]
	v_mfma_f32_16x16x32_bf16 v[60:63], v[132:135], v[194:197], v[60:63]
	v_mfma_f32_16x16x32_bf16 v[56:59], v[160:163], v[194:197], v[56:59]
	v_mfma_f32_16x16x32_bf16 v[44:47], v[132:135], v[202:205], v[44:47]
	v_mfma_f32_16x16x32_bf16 v[40:43], v[160:163], v[202:205], v[40:43]
	v_mfma_f32_16x16x32_bf16 v[28:31], v[132:135], v[224:227], v[28:31]
	v_mfma_f32_16x16x32_bf16 v[24:27], v[160:163], v[224:227], v[24:27]
	v_mfma_f32_16x16x32_bf16 v[12:15], v[132:135], v[232:235], v[12:15]
	v_mfma_f32_16x16x32_bf16 v[8:11], v[160:163], v[232:235], v[8:11]
	s_setprio 0
	s_setprio 1
	v_mfma_f32_16x16x32_bf16 v[52:55], v[164:167], v[190:193], v[52:55]
	v_mfma_f32_16x16x32_bf16 v[48:51], v[172:175], v[190:193], v[48:51]
	v_mfma_f32_16x16x32_bf16 v[36:39], v[164:167], v[198:201], v[36:39]
	v_mfma_f32_16x16x32_bf16 v[32:35], v[172:175], v[198:201], v[32:35]
	v_mfma_f32_16x16x32_bf16 v[20:23], v[164:167], v[206:209], v[20:23]
	v_mfma_f32_16x16x32_bf16 v[16:19], v[172:175], v[206:209], v[16:19]
	v_mfma_f32_16x16x32_bf16 v[4:7], v[164:167], v[228:231], v[4:7]
	v_mfma_f32_16x16x32_bf16 v[0:3], v[172:175], v[228:231], v[0:3]
	v_mfma_f32_16x16x32_bf16 v[52:55], v[168:171], v[194:197], v[52:55]
	v_mfma_f32_16x16x32_bf16 v[48:51], v[176:179], v[194:197], v[48:51]
	v_mfma_f32_16x16x32_bf16 v[36:39], v[168:171], v[202:205], v[36:39]
	v_mfma_f32_16x16x32_bf16 v[32:35], v[176:179], v[202:205], v[32:35]
	v_mfma_f32_16x16x32_bf16 v[20:23], v[168:171], v[224:227], v[20:23]
	v_mfma_f32_16x16x32_bf16 v[16:19], v[176:179], v[224:227], v[16:19]
	v_mfma_f32_16x16x32_bf16 v[4:7], v[168:171], v[232:235], v[4:7]
	v_mfma_f32_16x16x32_bf16 v[0:3], v[176:179], v[232:235], v[0:3]
	s_setprio 0
	s_barrier
	s_add_u32 s18, s18, 0x100
	s_addc_u32 s19, s19, 0
	s_add_u32 s23, s23, 0x100
	s_addc_u32 s29, s29, 0
	s_cmp_ge_u32 s34, s12
	s_mov_b32 s20, s34
	s_cbranch_scc0 .LBB0_738
.Lmy_kexit0:
	s_and_b64 vcc, exec, s[6:7]
	s_cbranch_vccz .LBB0_741
	s_barrier
